# fused sub3->sub4 counters moved to one cache line per row panel (cumulative across layers)
# speedup vs baseline: 1.0130x; 1.0044x over previous
.LBB0_148:
	s_and_b32 s0, s14, -8
	s_or_b32 s0, s0, s15
	s_load_dword s22, s[96:97], 0x0
	s_waitcnt lgkmcnt(0)
	s_cmp_eq_u32 s22, 0x200
	s_cbranch_scc0 .Lgw_skipall
	v_cmp_eq_u32_e64 s[22:23], 0, v124
	s_and_saveexec_b64 s[20:21], s[22:23]
	s_cbranch_execz .Lgw_done
	s_lshr_b32 s22, s0, 4
	s_lshl_b32 s22, s22, 12
	s_and_b32 s23, s0, 15
	s_lshl_b32 s23, s23, 7
	s_add_i32 s22, s22, s23
	s_addk_i32 s22, 0xc40
	s_add_i32 s43, s12, 1
	s_lshl_b32 s43, s43, 3
	v_mov_b32_e32 v0, s22
	s_lshl_b32 s1, s0, 2
	s_addk_i32 s1, 0x100
	v_mov_b32_e32 v1, s1
	global_load_dword v1, v1, s[4:5] sc1
	s_getreg_b32 s1, hwreg(HW_REG_XCC_ID, 0, 4)
	s_lshl_b32 s1, s1, 2
	s_lshl_b32 s1, 8, s1
	s_waitcnt vmcnt(0)
	v_readfirstlane_b32 s22, v1
	s_sub_i32 s1, s1, s22
	s_mov_b32 s23, 0
.Lgw_spin:
	global_load_dword v1, v0, s[4:5] sc1
	s_waitcnt vmcnt(0)
	v_readfirstlane_b32 s22, v1
	s_cmp_ge_u32 s22, s43
	s_cbranch_scc1 .Lgw_got
	s_sleep 1
	s_add_i32 s23, s23, 1
	s_cmp_lt_u32 s23, 0x800
	s_cbranch_scc1 .Lgw_spin

.Lsig_norel:
	s_lshr_b32 s98, s74, 6
	s_lshl_b32 s98, s98, 3
	s_and_b32 s99, s74, 7
	s_or_b32 s98, s98, s99
	s_lshr_b32 s99, s98, 4
	s_lshl_b32 s99, s99, 12
	s_and_b32 s98, s98, 15
	s_lshl_b32 s98, s98, 7
	s_add_i32 s98, s98, s99
	s_addk_i32 s98, 0xc40
	v_mov_b32_e32 v64, s98
	v_mov_b32_e32 v65, 1
	global_atomic_add v64, v65, s[4:5]
